# plus: attention score-minus-max subtractions and row-sum adds packed (v_pk_add_f32), bit-identical
# speedup vs baseline: 1.0069x; 1.0007x over previous
.LBB0_797:
	v_sub_f32_e32 v139, v139, v101
	v_sub_f32_e32 v170, v170, v101
	v_pk_add_f32 v[140:141], v[140:141], v[100:101] op_sel:[0,1] op_sel_hi:[1,1] neg_lo:[0,1] neg_hi:[0,1]
	v_pk_add_f32 v[142:143], v[142:143], v[100:101] op_sel:[0,1] op_sel_hi:[1,1] neg_lo:[0,1] neg_hi:[0,1]
	v_pk_add_f32 v[144:145], v[144:145], v[100:101] op_sel:[0,1] op_sel_hi:[1,1] neg_lo:[0,1] neg_hi:[0,1]
	v_pk_add_f32 v[146:147], v[146:147], v[100:101] op_sel:[0,1] op_sel_hi:[1,1] neg_lo:[0,1] neg_hi:[0,1]
	v_pk_add_f32 v[148:149], v[148:149], v[100:101] op_sel:[0,1] op_sel_hi:[1,1] neg_lo:[0,1] neg_hi:[0,1]
	v_pk_add_f32 v[150:151], v[150:151], v[100:101] op_sel:[0,1] op_sel_hi:[1,1] neg_lo:[0,1] neg_hi:[0,1]
	v_pk_add_f32 v[152:153], v[152:153], v[100:101] op_sel:[0,1] op_sel_hi:[1,1] neg_lo:[0,1] neg_hi:[0,1]
	v_pk_add_f32 v[154:155], v[154:155], v[100:101] op_sel:[0,1] op_sel_hi:[1,1] neg_lo:[0,1] neg_hi:[0,1]
	v_pk_add_f32 v[156:157], v[156:157], v[100:101] op_sel:[0,1] op_sel_hi:[1,1] neg_lo:[0,1] neg_hi:[0,1]
	v_pk_add_f32 v[158:159], v[158:159], v[100:101] op_sel:[0,1] op_sel_hi:[1,1] neg_lo:[0,1] neg_hi:[0,1]
	v_pk_add_f32 v[160:161], v[160:161], v[100:101] op_sel:[0,1] op_sel_hi:[1,1] neg_lo:[0,1] neg_hi:[0,1]
	v_pk_add_f32 v[162:163], v[162:163], v[100:101] op_sel:[0,1] op_sel_hi:[1,1] neg_lo:[0,1] neg_hi:[0,1]
	v_pk_add_f32 v[164:165], v[164:165], v[100:101] op_sel:[0,1] op_sel_hi:[1,1] neg_lo:[0,1] neg_hi:[0,1]
	v_pk_add_f32 v[166:167], v[166:167], v[100:101] op_sel:[0,1] op_sel_hi:[1,1] neg_lo:[0,1] neg_hi:[0,1]
	v_pk_add_f32 v[168:169], v[168:169], v[100:101] op_sel:[0,1] op_sel_hi:[1,1] neg_lo:[0,1] neg_hi:[0,1]
	v_exp_f32_e32 v50, v140
	v_exp_f32_e32 v51, v164
	v_exp_f32_e32 v52, v139
	v_exp_f32_e32 v53, v162
	v_exp_f32_e32 v54, v143
	v_exp_f32_e32 v55, v167
	v_exp_f32_e32 v56, v141
	v_exp_f32_e32 v57, v165
	v_pk_add_f32 v[34:35], v[50:51], 0 op_sel_hi:[1,0]
	s_nop 0
	v_pk_add_f32 v[34:35], v[52:53], v[34:35]
	v_cvt_pk_bf16_f32 v39, v54, v56
	v_pk_add_f32 v[34:35], v[54:55], v[34:35]
	ds_read_b128 v[46:49], v0 offset:23040
	v_pk_add_f32 v[58:59], v[56:57], v[34:35]
	v_exp_f32_e32 v60, v144
	v_exp_f32_e32 v61, v168
	v_exp_f32_e32 v62, v142
	v_exp_f32_e32 v63, v166
	v_exp_f32_e32 v64, v147
	v_exp_f32_e32 v65, v170
	v_exp_f32_e32 v140, v146
	v_exp_f32_e32 v141, v169
	v_exp_f32_e32 v142, v150
	v_exp_f32_e32 v144, v148
	v_exp_f32_e32 v146, v152
	v_exp_f32_e32 v148, v151
	v_exp_f32_e32 v150, v154
	ds_read_b128 v[34:37], v0 offset:18432
	ds_read_b128 v[42:45], v0 offset:18464
	v_exp_f32_e32 v152, v153
	v_exp_f32_e32 v154, v149
	v_cvt_pk_bf16_f32 v38, v50, v52
	v_cvt_pk_bf16_f32 v40, v60, v62
	v_cvt_pk_bf16_f32 v41, v64, v140
	s_waitcnt lgkmcnt(1)
	s_nop 0
	v_mfma_f32_32x32x16_bf16 v[18:33], v[34:37], v[38:41], v[18:33]
	v_exp_f32_e32 v50, v145
	v_cvt_pk_bf16_f32 v34, v142, v144
	v_cvt_pk_bf16_f32 v35, v146, v148
	v_cvt_pk_bf16_f32 v36, v150, v152
	v_cvt_pk_bf16_f32 v37, v154, v50
	s_waitcnt lgkmcnt(0)
	s_nop 0
	v_mfma_f32_32x32x16_bf16 v[18:33], v[42:45], v[34:37], v[18:33]
	v_exp_f32_e32 v143, v156
	v_exp_f32_e32 v145, v155
	v_exp_f32_e32 v147, v158
	ds_read_b128 v[42:45], v0 offset:23072
	v_mfma_f32_32x32x16_bf16 v[2:17], v[46:49], v[38:41], v[2:17]
	v_exp_f32_e32 v149, v157
	v_exp_f32_e32 v151, v161
	v_exp_f32_e32 v153, v160
	ds_read_b128 v[38:41], v0 offset:18496
	s_waitcnt lgkmcnt(1)
	v_mfma_f32_32x32x16_bf16 v[2:17], v[42:45], v[34:37], v[2:17]
	v_exp_f32_e32 v155, v163
	v_cvt_pk_bf16_f32 v34, v51, v53
	v_cvt_pk_bf16_f32 v35, v55, v57
	v_cvt_pk_bf16_f32 v36, v61, v63
	v_cvt_pk_bf16_f32 v37, v65, v141
	ds_read_b128 v[42:45], v0 offset:18528
	ds_read_b128 v[46:49], v0 offset:23104
	s_waitcnt lgkmcnt(2)
	v_mfma_f32_32x32x16_bf16 v[18:33], v[38:41], v[34:37], v[18:33]
	v_exp_f32_e32 v51, v159
	v_cvt_pk_bf16_f32 v38, v143, v145
	v_cvt_pk_bf16_f32 v39, v147, v149
	v_cvt_pk_bf16_f32 v40, v151, v153
	v_cvt_pk_bf16_f32 v41, v155, v51
	s_waitcnt lgkmcnt(1)
	s_nop 0
	v_mfma_f32_32x32x16_bf16 v[18:33], v[42:45], v[38:41], v[18:33]
	v_pk_add_f32 v[42:43], v[60:61], v[58:59]
	s_nop 0
	v_pk_add_f32 v[42:43], v[62:63], v[42:43]
	s_nop 0
	v_pk_add_f32 v[42:43], v[64:65], v[42:43]
	s_nop 0
	v_pk_add_f32 v[42:43], v[140:141], v[42:43]
	s_nop 0
	v_pk_add_f32 v[42:43], v[142:143], v[42:43]
	s_nop 0
	v_pk_add_f32 v[52:53], v[144:145], v[42:43]
	ds_read_b128 v[42:45], v0 offset:23136
	s_waitcnt lgkmcnt(1)
	v_mfma_f32_32x32x16_bf16 v[2:17], v[46:49], v[34:37], v[2:17]
	v_pk_add_f32 v[34:35], v[146:147], v[52:53]
	s_nop 0
	v_pk_add_f32 v[34:35], v[148:149], v[34:35]
	s_nop 0
	v_pk_add_f32 v[34:35], v[150:151], v[34:35]
	s_nop 0
	v_pk_add_f32 v[34:35], v[152:153], v[34:35]
	s_waitcnt lgkmcnt(0)
	v_mfma_f32_32x32x16_bf16 v[2:17], v[42:45], v[38:41], v[2:17]
	v_pk_add_f32 v[34:35], v[154:155], v[34:35]
	s_nop 0
	v_pk_add_f32 v[34:35], v[50:51], v[34:35]
	v_add_f32_e32 v0, v34, v35
	v_add_f32_e32 v97, v97, v0
